# P1 column tiles taken in reverse order so the q / k,v slices P2 reads first are written last
# baseline (speedup 1.0000x reference)
.LBB0_210:
	s_mov_b32 s50, s2
	s_movk_i32 s0, 0x400
	v_mov_b32_e32 v12, v193
	s_cmpk_lt_i32 s50, 0x6e8
	s_cselect_b64 s[4:5], -1, 0
	s_cmpk_gt_i32 s50, 0x6e7
	v_readfirstlane_b32 s10, v12
	s_cbranch_scc1 .LBB0_212
	s_ashr_i32 s1, s50, 31
	s_lshr_b32 s1, s1, 29
	s_add_i32 s1, s50, s1
	s_ashr_i32 s3, s1, 3
	s_and_b32 s1, s1, -8
	s_sub_i32 s1, s50, s1
	s_cmp_lt_i32 s1, 0
	s_movk_i32 s6, 0xde
	s_cselect_b32 s6, s6, 0xdd
	s_mul_i32 s1, s1, s6
	s_add_i32 s1, s1, s3
	s_mul_hi_i32 s3, s1, 0x4ec4ec4f
	s_lshr_b32 s6, s3, 31
	s_ashr_i32 s3, s3, 6
	s_add_i32 s3, s3, s6
	s_lshl_b32 s8, s3, 3
	s_sub_i32 s6, 0x44, s8
	s_min_u32 s9, s6, 8
	s_mulk_i32 s3, 0xd0
	s_sub_i32 s1, s1, s3
	v_cvt_f32_ubyte0_e32 v1, s9
	v_cvt_f32_i32_e32 v0, s1
	v_rcp_iflag_f32_e32 v2, v1
	s_ashr_i32 s3, s1, 30
	s_or_b32 s3, s3, 1
	v_mul_f32_e32 v2, v0, v2
	v_trunc_f32_e32 v2, v2
	v_fma_f32 v0, -v2, v1, v0
	v_cvt_i32_f32_e32 v2, v2
	v_cmp_ge_f32_e64 s[6:7], |v0|, v1
	s_and_b64 s[6:7], s[6:7], exec
	s_cselect_b32 s3, s3, 0
	v_readfirstlane_b32 s6, v2
	s_add_i32 s3, s6, s3
	s_sext_i32_i16 s30, s3
	s_mul_i32 s3, s3, s9
	s_sub_i32 s1, s1, s3
	s_sext_i32_i16 s1, s1
	s_add_i32 s31, s8, s1
	s_sub_i32 s30, 25, s30

.LBB0_218:
	s_add_i32 s43, s43, 1
	s_mul_i32 s0, s43, s47
	s_mul_hi_u32 s1, s43, s34
	s_add_i32 s1, s1, s0
	s_mul_i32 s0, s43, s34
	s_add_u32 s10, s0, s50
	s_addc_u32 s11, s1, s42
	v_mov_b64_e32 v[0:1], 0x6e8
	v_cmp_lt_i64_e64 s[0:1], s[10:11], v[0:1]
	v_mov_b64_e32 v[0:1], 0x6e7
	v_cmp_gt_i64_e32 vcc, s[10:11], v[0:1]
	s_cbranch_vccnz .LBB0_220
	s_ashr_i32 s11, s10, 31
	s_lshr_b32 s11, s11, 29
	s_add_i32 s11, s10, s11
	s_ashr_i32 s24, s11, 3
	s_and_b32 s11, s11, -8
	s_sub_i32 s10, s10, s11
	s_cmp_lt_i32 s10, 0
	s_movk_i32 s11, 0xde
	s_cselect_b32 s11, s11, 0xdd
	s_mul_i32 s10, s10, s11
	s_add_i32 s10, s10, s24
	s_mul_hi_i32 s11, s10, 0x4ec4ec4f
	s_lshr_b32 s24, s11, 31
	s_ashr_i32 s11, s11, 6
	s_add_i32 s11, s11, s24
	s_lshl_b32 s24, s11, 3
	s_sub_i32 s25, 0x44, s24
	s_min_i32 s25, s25, 8
	s_abs_i32 s28, s25
	v_cvt_f32_u32_e32 v0, s28
	s_sub_i32 s48, 0, s28
	s_mulk_i32 s11, 0xd0
	s_sub_i32 s10, s10, s11
	v_rcp_iflag_f32_e32 v0, v0
	s_abs_i32 s11, s10
	s_xor_b32 s29, s10, s25
	s_ashr_i32 s29, s29, 31
	v_mul_f32_e32 v0, 0x4f7ffffe, v0
	v_cvt_u32_f32_e32 v0, v0
	s_nop 0
	v_readfirstlane_b32 s49, v0
	s_mul_i32 s48, s48, s49
	s_mul_hi_u32 s48, s49, s48
	s_add_i32 s49, s49, s48
	s_mul_hi_u32 s48, s11, s49
	s_mul_i32 s49, s48, s28
	s_sub_i32 s11, s11, s49
	s_add_i32 s68, s48, 1
	s_sub_i32 s49, s11, s28
	s_cmp_ge_u32 s11, s28
	s_cselect_b32 s48, s68, s48
	s_cselect_b32 s11, s49, s11
	s_add_i32 s49, s48, 1
	s_cmp_ge_u32 s11, s28
	s_cselect_b32 s11, s49, s48
	s_xor_b32 s11, s11, s29
	s_sub_i32 s72, s11, s29
	s_mul_i32 s11, s72, s25
	s_sub_i32 s10, s10, s11
	s_add_i32 s73, s24, s10
	s_sub_i32 s72, 25, s72
